# no full vmcnt drain between residual GEMM tile loop and sample-row small GEMM
# baseline (speedup 1.0000x reference)
; #define LAS __attribute__((address_space(3)))
; __device__ __forceinline__ void small_gemm_res(LAS unsigned char* lds, const bf16_t* A, const bf16_t* Bt, int K, int unit, bf16_t* XB, float* SS, float sc) {
;     int tid = threadIdx.x; asm volatile("" : "+v"(tid));
;     const int wave = __builtin_amdgcn_readfirstlane(tid >> 6), lane = tid & 63, li = lane & 15, g4 = lane >> 4;
;     const int ux = unit & 7, ur = unit >> 3;
;     const int ct = 2 * ux + (ur & 1), rt = ur >> 1, row0 = TP + 32 * rt, col0 = 64 * ct;
;     const int KS = K >> 8;
;     const int row = tid >> 4, c4 = (tid & 15) * 4;
;     const size_t off = (size_t)(row0 + row) * D + col0 + c4;
;     const u32x2 xw = *(const u32x2*)(XB + off);
;     f32x4 acc[2][4];
; #pragma unroll
;     for (int m = 0; m < 2; ++m)
; #pragma unroll
;         for (int t = 0; t < 4; ++t) acc[m][t] = (f32x4){0.f, 0.f, 0.f, 0.f};
;     const bf16_t* ap = A + (size_t)(row0 + li) * K + 8 * g4 + 32 * wave * KS;
;     const bf16_t* bp = Bt + (size_t)(col0 + li) * K + 8 * g4 + 32 * wave * KS;
; #pragma unroll 6
;     for (int ks = 0; ks < KS; ++ks) {
;         const bf16x8 a0 = *(const bf16x8*)(ap + 32 * ks), a1 = *(const bf16x8*)(ap + (size_t)16 * K + 32 * ks);
; #pragma unroll
;         for (int t = 0; t < 4; ++t) { const bf16x8 b = *(const bf16x8*)(bp + (size_t)16 * t * K + 32 * ks);
;             acc[0][t] = __builtin_amdgcn_mfma_f32_16x16x32_bf16(b, a0, acc[0][t], 0, 0, 0); acc[1][t] = __builtin_amdgcn_mfma_f32_16x16x32_bf16(b, a1, acc[1][t], 0, 0, 0); }
;     }
;     LAS float* red = (LAS float*)lds;
; #pragma unroll
;     for (int m = 0; m < 2; ++m)
; #pragma unroll
;         for (int t = 0; t < 4; ++t) *(LAS f32x4*)(red + (wave * 32 + 16 * m + li) * 64 + 16 * t + 4 * g4) = acc[m][t];
;     __syncthreads();
;     f32x4 sum = *(LAS f32x4*)(red + row * 64 + c4);
; #pragma unroll
;     for (int w = 1; w < 8; ++w) sum += *(LAS f32x4*)(red + (w * 32 + row) * 64 + c4);
;     f32x4 x = (f32x4){bf_lo(xw.x), bf_hi(xw.x), bf_lo(xw.y), bf_hi(xw.y)}; x += sum * sc;
;     u32x2 w; w.x = cvt_pk_bf16(x[0], x[1]); w.y = cvt_pk_bf16(x[2], x[3]); *(u32x2*)(XB + off) = w;
;     float ss = (x[0] * x[0] + x[1] * x[1]) + (x[2] * x[2] + x[3] * x[3]);
;     ss += __shfl_xor(ss, 1); ss += __shfl_xor(ss, 2); ss += __shfl_xor(ss, 4); ss += __shfl_xor(ss, 8);
.LBB0_662:
	s_lshr_b32 s14, s7, 8
	s_lshl_b32 s6, s7, 5
	v_xor_b32_e32 v0, 1, v210
	s_mul_i32 s2, s7, 0x60
	v_cmp_lt_i32_e32 vcc, v0, v130
	s_add_u32 s2, s2, s28
	s_addc_u32 s3, 0, s29
	v_cndmask_b32_e32 v0, v210, v0, vcc
	v_lshlrev_b32_e32 v54, 2, v0
	v_xor_b32_e32 v0, 2, v210
	s_add_u32 s2, s26, s2
	v_cmp_lt_i32_e32 vcc, v0, v130
	s_addc_u32 s3, s27, s3
	s_lshl_b32 s4, s7, 6
	v_cndmask_b32_e32 v0, v210, v0, vcc
	s_add_u32 s4, s4, s28
	v_lshlrev_b32_e32 v55, 2, v0
	v_xor_b32_e32 v0, 4, v210
	s_addc_u32 s5, 0, s29
	v_cmp_lt_i32_e32 vcc, v0, v130
	s_add_u32 s4, s26, s4
	s_addc_u32 s5, s27, s5
	v_cndmask_b32_e32 v0, v210, v0, vcc
	v_lshlrev_b32_e32 v56, 2, v0
	v_xor_b32_e32 v0, 8, v210
	s_add_u32 s6, s6, s28
	v_cmp_lt_i32_e32 vcc, v0, v130
	s_addc_u32 s15, 0, s29
	s_add_u32 s26, s26, s6
	v_cndmask_b32_e32 v0, v210, v0, vcc
	s_mov_b32 s25, s24
	s_mov_b32 s0, s24
	s_mov_b32 s1, s24
	v_lshlrev_b32_e32 v57, 2, v0
	s_addc_u32 s27, s27, s15
	s_lshl_b32 s15, s68, 1
	s_lshl_b32 s16, s7, 1
	s_mov_b32 s17, s68
	v_readlane_b32 s36, v254, 45
	s_movk_i32 s48, 0xc0
	s_mov_b32 s39, 0x20000
	s_mov_b32 s40, 0x28000
	s_mov_b32 s41, 0x30000
	s_mov_b32 s42, 0x38000
	s_mov_b32 s43, 0x60000
	s_mov_b64 s[54:55], 0x100
	s_mov_b32 s45, s46
	s_barrier
	s_branch .LBB0_664
